# P5 DSA attention: selection mask applied by v_bfe_i32+v_bfi_b32 instead of and/cmp/nop/cndmask (no VCC hazard), on top of the indexer bisection-count rewrite
# speedup vs baseline: 1.0012x; 1.0012x over previous
; __device__ __forceinline__ void mask_bits(f32x16& p0, f32x16& p1, unsigned long long mk, int hi) {
;     const float NEG = -__builtin_inff();
;     const unsigned lo = (unsigned)mk >> (4 * hi), hh = (unsigned)(mk >> 32) >> (4 * hi);
; #pragma unroll
;     for (int r = 0; r < 16; ++r) {
;         const int c = (r & 3) + 8 * (r >> 2);
;         if (!(lo & (1u << c))) p0[r] = NEG;
;         if (!(hh & (1u << c))) p1[r] = NEG;
;     }
; }
; __device__ __forceinline__ void partialSM(f32x16& p0, f32x16& p1, float& m_reg, float& mn, float& alpha) {
;     float pmax = p0[0];
; #pragma unroll
;     for (int r = 1; r < 16; ++r) pmax = fmaxf(pmax, p0[r]);
; #pragma unroll
;     for (int r = 0; r < 16; ++r) pmax = fmaxf(pmax, p1[r]);
;     { auto rr = __builtin_amdgcn_permlane32_swap(__float_as_uint(pmax), __float_as_uint(pmax), false, false);
;       pmax = fmaxf(__uint_as_float(rr[0]), __uint_as_float(rr[1])); }
;     constexpr float C2 = 1.4426950408889634f * SM_SCALE;
;     if (__builtin_expect(__all((pmax - m_reg) * SM_SCALE <= THR), 1)) { mn = m_reg; alpha = 1.f; }
; template <int KB, int MODE>
; __device__ __forceinline__ void qkt(f32x16& p0, f32x16& p1, const char* K_lds, int r32, int hi, const bf16x8* qr, float bz0, float bz1) {
;     ...
;     const char* kb[4];
; #pragma unroll
;     for (int dd = 0; dd < 4; ++dd) kb[dd] = K_lds + KB * SHM_K + KSWZ(r32, (dd * 16 + hi * 8) * 2);
; #pragma unroll
;     for (int d0 = 0; d0 < 8; ++d0) { const char* a = kb[d0 & 3] + (d0 >> 2) * 128;
;         bf16x8 b0 = *reinterpret_cast<const bf16x8*>(a);
;         bf16x8 b1 = *reinterpret_cast<const bf16x8*>(a + 32 * 256);
;         p0 = __builtin_amdgcn_mfma_f32_32x32x16_bf16(b0, qr[d0], p0, 0, 0, 0);
;         p1 = __builtin_amdgcn_mfma_f32_32x32x16_bf16(b1, qr[d0], p1, 0, 0, 0); }
.LBB0_1221:
	s_lshr_b32 s44, s21, 6
	s_lshl_b32 s6, s44, 2
	v_or_b32_e32 v1, s6, v214
	v_lshlrev_b32_e32 v2, 9, v1
	global_load_dwordx2 v[204:205], v2, s[22:23]
	ds_read_b128 v[4:7], v221 offset:32768
	ds_read_b128 v[36:39], v221 offset:32896
	ds_read_b128 v[20:23], v221 offset:40960
	ds_read_b128 v[40:43], v221 offset:41088
	ds_read_b128 v[44:47], v222 offset:32768
	ds_read_b128 v[48:51], v222 offset:32896
	s_waitcnt vmcnt(8) lgkmcnt(5)
	v_mfma_f32_32x32x16_bf16 v[4:19], v[4:7], v[158:161], 0
	s_waitcnt lgkmcnt(3)
	v_mfma_f32_32x32x16_bf16 v[20:35], v[20:23], v[158:161], 0
	s_waitcnt vmcnt(7) lgkmcnt(1)
	v_mfma_f32_32x32x16_bf16 v[4:19], v[44:47], v[154:157], v[4:19]
	ds_read_b128 v[44:47], v222 offset:40960
	ds_read_b128 v[52:55], v222 offset:41088
	s_waitcnt lgkmcnt(1)
	v_mfma_f32_32x32x16_bf16 v[20:35], v[44:47], v[154:157], v[20:35]
	ds_read_b128 v[44:47], v223 offset:32768
	ds_read_b128 v[56:59], v223 offset:32896
	s_waitcnt vmcnt(6) lgkmcnt(1)
	v_mfma_f32_32x32x16_bf16 v[4:19], v[44:47], v[150:153], v[4:19]
	ds_read_b128 v[44:47], v223 offset:40960
	ds_read_b128 v[60:63], v223 offset:41088
	s_waitcnt lgkmcnt(1)
	v_mfma_f32_32x32x16_bf16 v[20:35], v[44:47], v[150:153], v[20:35]
	ds_read_b128 v[44:47], v224 offset:32768
	ds_read_b128 v[64:67], v224 offset:32896
	s_waitcnt vmcnt(5) lgkmcnt(1)
	v_mfma_f32_32x32x16_bf16 v[4:19], v[44:47], v[146:149], v[4:19]
	ds_read_b128 v[44:47], v224 offset:40960
	ds_read_b128 v[68:71], v224 offset:41088
	s_waitcnt lgkmcnt(1)
	v_mfma_f32_32x32x16_bf16 v[20:35], v[44:47], v[146:149], v[20:35]
	s_waitcnt vmcnt(4)
	v_mfma_f32_32x32x16_bf16 v[4:19], v[36:39], v[174:177], v[4:19]
	s_waitcnt vmcnt(0)
	v_lshrrev_b32_e32 v36, v215, v204
	v_lshrrev_b32_e32 v37, v215, v205
	v_mfma_f32_32x32x16_bf16 v[20:35], v[40:43], v[174:177], v[20:35]
	v_mfma_f32_32x32x16_bf16 v[4:19], v[48:51], v[170:173], v[4:19]
	v_mfma_f32_32x32x16_bf16 v[20:35], v[52:55], v[170:173], v[20:35]
	v_mfma_f32_32x32x16_bf16 v[4:19], v[56:59], v[166:169], v[4:19]
	v_mfma_f32_32x32x16_bf16 v[20:35], v[60:63], v[166:169], v[20:35]
	v_mfma_f32_32x32x16_bf16 v[4:19], v[64:67], v[162:165], v[4:19]
	s_waitcnt lgkmcnt(0)
	v_mfma_f32_32x32x16_bf16 v[20:35], v[68:71], v[162:165], v[20:35]
	s_nop 9
	v_bfe_i32 v1, v36, 0, 1
	v_bfi_b32 v1, v1, v4, v225
	v_bfe_i32 v4, v37, 0, 1
	v_bfi_b32 v4, v4, v20, v225
	v_bfe_i32 v20, v36, 1, 1
	v_bfi_b32 v20, v20, v5, v225
	v_bfe_i32 v5, v37, 1, 1
	v_bfi_b32 v5, v5, v21, v225
	v_bfe_i32 v21, v36, 2, 1
	v_bfi_b32 v21, v21, v6, v225
	v_bfe_i32 v6, v37, 2, 1
	v_bfi_b32 v6, v6, v22, v225
	v_bfe_i32 v22, v36, 3, 1
	v_bfi_b32 v22, v22, v7, v225
	v_bfe_i32 v7, v37, 3, 1
	v_bfi_b32 v7, v7, v23, v225
	v_bfe_i32 v23, v36, 8, 1
	v_bfi_b32 v23, v23, v8, v225
	v_bfe_i32 v8, v37, 8, 1
	v_bfi_b32 v8, v8, v24, v225
	v_bfe_i32 v24, v36, 9, 1
	v_bfi_b32 v24, v24, v9, v225
	v_bfe_i32 v9, v37, 9, 1
	v_bfi_b32 v9, v9, v25, v225
	v_bfe_i32 v25, v36, 10, 1
	v_bfi_b32 v25, v25, v10, v225
	v_bfe_i32 v10, v37, 10, 1
	v_bfi_b32 v10, v10, v26, v225
	v_bfe_i32 v26, v36, 11, 1
	v_bfi_b32 v26, v26, v11, v225
	v_bfe_i32 v11, v37, 11, 1
	v_bfi_b32 v11, v11, v27, v225
	v_bfe_i32 v27, v36, 16, 1
	v_bfi_b32 v27, v27, v12, v225
	v_bfe_i32 v12, v37, 16, 1
	v_bfi_b32 v12, v12, v28, v225
	v_bfe_i32 v28, v36, 17, 1
	v_bfi_b32 v28, v28, v13, v225
	v_bfe_i32 v13, v37, 17, 1
	v_bfi_b32 v13, v13, v29, v225
	v_bfe_i32 v29, v36, 18, 1
	v_bfi_b32 v29, v29, v14, v225
	v_bfe_i32 v14, v37, 18, 1
	v_bfi_b32 v14, v14, v30, v225
	v_bfe_i32 v30, v36, 19, 1
	v_bfi_b32 v30, v30, v15, v225
	v_bfe_i32 v15, v37, 19, 1
	v_bfi_b32 v15, v15, v31, v225
	v_bfe_i32 v31, v36, 24, 1
	v_bfi_b32 v31, v31, v16, v225
	v_bfe_i32 v16, v37, 24, 1
	v_bfi_b32 v16, v16, v32, v225
	v_bfe_i32 v32, v36, 25, 1
	v_bfi_b32 v32, v32, v17, v225
	v_bfe_i32 v17, v37, 25, 1
	v_bfi_b32 v17, v17, v33, v225
	v_bfe_i32 v33, v36, 26, 1
	v_bfi_b32 v33, v33, v18, v225
	v_bfe_i32 v18, v37, 26, 1
	v_bfi_b32 v18, v18, v34, v225
	v_and_b32_e32 v34, 0x8000000, v36
	v_cmp_ne_u32_e32 vcc, 0, v34
	v_max_f32_e32 v36, v1, v1
	s_nop 0
	s_nop 1
	v_cndmask_b32_e32 v34, v225, v19, vcc
	v_bfe_i32 v19, v37, 27, 1
	v_bfi_b32 v19, v19, v35, v225
	v_max_f32_e32 v35, v20, v20
	v_max_f32_e32 v35, v36, v35
	v_max3_f32 v35, v35, v21, v22
	v_max3_f32 v35, v35, v23, v24
	v_max3_f32 v35, v35, v25, v26
	v_max3_f32 v35, v35, v27, v28
	v_max3_f32 v35, v35, v29, v30
	v_max3_f32 v35, v35, v31, v32
	v_max3_f32 v35, v35, v33, v34
	v_max3_f32 v35, v35, v4, v5
	v_max3_f32 v35, v35, v6, v7
	v_max3_f32 v35, v35, v8, v9
	v_max3_f32 v35, v35, v10, v11
	v_max3_f32 v35, v35, v12, v13
	v_max3_f32 v35, v35, v14, v15
	v_max3_f32 v35, v35, v16, v17
	v_max3_f32 v35, v35, v18, v19
	v_mov_b32_e32 v36, v35
	s_nop 1
	v_permlane32_swap_b32_e32 v35, v36
	v_max_f32_e32 v36, v36, v36
	v_max_f32_e32 v35, v35, v35
	v_max_f32_e32 v35, v35, v36
	v_add_f32_e32 v36, 0x7149f2ca, v35
	v_mul_f32_e32 v36, 0x3db504f3, v36
	v_cmp_ge_f32_e32 vcc, s41, v36
	s_cmp_eq_u64 vcc, exec
	s_cbranch_scc0 .LBB0_1384
	v_mov_b32_e32 v203, 1.0
	v_mov_b32_e32 v201, 0xf149f2ca
	s_andn2_b64 vcc, exec, s[28:29]
	s_cbranch_vccnz .LBB0_1224

; __device__ __forceinline__ void finishSM(f32x16& p0, f32x16& p1, float alpha, float& l_reg, bf16x8& pa0, bf16x8& pa1, bf16x8& pa2, bf16x8& pa3) {
; #pragma unroll
;     for (int r = 0; r < 16; ++r) p1[r] = __builtin_amdgcn_exp2f(p1[r]);
;     float ps = 0;
; #pragma unroll
;     for (int r = 0; r < 16; ++r) ps += p0[r];
; #pragma unroll
;     for (int r = 0; r < 16; ++r) ps += p1[r];
;     { auto rr = __builtin_amdgcn_permlane32_swap(__float_as_uint(ps), __float_as_uint(ps), false, false);
;       ps = __uint_as_float(rr[0]) + __uint_as_float(rr[1]); }
;     l_reg = l_reg * alpha + ps;
;     ...
;     PK4(p0, 0, pa0); PK4(p0, 8, pa1); PK4(p1, 0, pa2); PK4(p1, 8, pa3);
; template <int KB, int MODE>
; __device__ __forceinline__ void qkt(f32x16& p0, f32x16& p1, const char* K_lds, int r32, int hi, const bf16x8* qr, float bz0, float bz1) {
;     ...
;     const char* kb[4];
; #pragma unroll
;     for (int dd = 0; dd < 4; ++dd) kb[dd] = K_lds + KB * SHM_K + KSWZ(r32, (dd * 16 + hi * 8) * 2);
; #pragma unroll
;     for (int d0 = 0; d0 < 8; ++d0) { const char* a = kb[d0 & 3] + (d0 >> 2) * 128;
;         bf16x8 b0 = *reinterpret_cast<const bf16x8*>(a);
;         bf16x8 b1 = *reinterpret_cast<const bf16x8*>(a + 32 * 256);
;         p0 = __builtin_amdgcn_mfma_f32_32x32x16_bf16(b0, qr[d0], p0, 0, 0, 0);
;         p1 = __builtin_amdgcn_mfma_f32_32x32x16_bf16(b1, qr[d0], p1, 0, 0, 0); }
.LBB0_1228:
	global_load_dwordx2 v[132:133], v[208:209], off
	ds_read_b128 v[4:7], v221 offset:49152
	ds_read_b128 v[8:11], v221 offset:49280
	v_add_f32_e32 v129, 0, v128
	v_exp_f32_e32 v186, v186
	v_exp_f32_e32 v187, v187
	s_waitcnt lgkmcnt(1)
	v_mfma_f32_32x32x16_bf16 v[82:97], v[4:7], v[158:161], 0
	ds_read_b128 v[4:7], v222 offset:49152
	ds_read_b128 v[12:15], v222 offset:49280
	v_exp_f32_e32 v184, v184
	v_exp_f32_e32 v185, v185
	v_exp_f32_e32 v182, v182
	v_exp_f32_e32 v183, v183
	v_exp_f32_e32 v180, v180
	v_exp_f32_e32 v181, v181
	s_waitcnt lgkmcnt(1)
	v_mfma_f32_32x32x16_bf16 v[82:97], v[4:7], v[154:157], v[82:97]
	ds_read_b128 v[4:7], v221 offset:57344
	ds_read_b128 v[134:137], v221 offset:57472
	v_exp_f32_e32 v178, v178
	v_exp_f32_e32 v179, v179
	s_waitcnt lgkmcnt(1)
	v_mfma_f32_32x32x16_bf16 v[98:113], v[4:7], v[158:161], 0
	ds_read_b128 v[4:7], v222 offset:57344
	ds_read_b128 v[138:141], v222 offset:57472
	s_waitcnt lgkmcnt(1)
	v_mfma_f32_32x32x16_bf16 v[98:113], v[4:7], v[154:157], v[98:113]
	ds_read_b128 v[4:7], v223 offset:49152
	ds_read_b128 v[142:145], v223 offset:49280
	s_waitcnt lgkmcnt(1)
	v_mfma_f32_32x32x16_bf16 v[82:97], v[4:7], v[150:153], v[82:97]
	ds_read_b128 v[4:7], v223 offset:57344
	ds_read_b128 v[194:197], v223 offset:57472
	s_waitcnt lgkmcnt(1)
	v_mfma_f32_32x32x16_bf16 v[98:113], v[4:7], v[150:153], v[98:113]
	ds_read_b128 v[4:7], v224 offset:49152
	ds_read_b128 v[230:233], v224 offset:49280
	ds_read_b128 v[234:237], v224 offset:57344
	ds_read_b128 v[238:241], v224 offset:57472
	v_cvt_pk_bf16_f32 v128, v128, v1
	v_add_f32_e32 v1, v1, v129
	v_add_f32_e32 v1, v126, v1
	v_add_f32_e32 v1, v123, v1
	v_add_f32_e32 v1, v122, v1
	v_add_f32_e32 v1, v125, v1
	s_waitcnt lgkmcnt(3)
	v_mfma_f32_32x32x16_bf16 v[82:97], v[4:7], v[146:149], v[82:97]
	v_add_f32_e32 v1, v124, v1
	v_add_f32_e32 v1, v127, v1
	v_add_f32_e32 v1, v114, v1
	v_add_f32_e32 v1, v115, v1
	v_add_f32_e32 v1, v116, v1
	v_add_f32_e32 v1, v117, v1
	v_exp_f32_e32 v4, v192
	s_waitcnt lgkmcnt(1)
	v_mfma_f32_32x32x16_bf16 v[98:113], v[234:237], v[146:149], v[98:113]
	v_add_f32_e32 v1, v118, v1
	v_exp_f32_e32 v5, v193
	v_add_f32_e32 v1, v119, v1
	v_exp_f32_e32 v6, v190
	v_add_f32_e32 v1, v120, v1
	v_exp_f32_e32 v7, v191
	v_add_f32_e32 v1, v121, v1
	v_mfma_f32_32x32x16_bf16 v[82:97], v[8:11], v[174:177], v[82:97]
	v_cvt_pk_bf16_f32 v129, v126, v123
	v_exp_f32_e32 v126, v188
	v_add_f32_e32 v1, v4, v1
	v_cvt_pk_bf16_f32 v130, v122, v125
	v_cvt_pk_bf16_f32 v131, v124, v127
	v_exp_f32_e32 v127, v189
	v_add_f32_e32 v1, v5, v1
	v_mfma_f32_32x32x16_bf16 v[98:113], v[134:137], v[174:177], v[98:113]
	v_add_f32_e32 v1, v6, v1
	v_add_f32_e32 v1, v7, v1
	v_add_f32_e32 v1, v126, v1
	v_add_f32_e32 v1, v127, v1
	v_add_f32_e32 v1, v186, v1
	v_add_f32_e32 v1, v187, v1
	v_add_f32_e32 v1, v184, v1
	v_mfma_f32_32x32x16_bf16 v[82:97], v[12:15], v[170:173], v[82:97]
	v_add_f32_e32 v1, v185, v1
	v_add_f32_e32 v1, v182, v1
	v_add_f32_e32 v1, v183, v1
	v_add_f32_e32 v1, v180, v1
	v_add_f32_e32 v1, v181, v1
	v_add_f32_e32 v1, v178, v1
	v_add_f32_e32 v228, v179, v1
	v_mfma_f32_32x32x16_bf16 v[98:113], v[138:141], v[170:173], v[98:113]
	v_mov_b32_e32 v229, v228
	v_cvt_pk_bf16_f32 v122, v114, v115
	v_cvt_pk_bf16_f32 v123, v116, v117
	v_cvt_pk_bf16_f32 v124, v118, v119
	v_cvt_pk_bf16_f32 v125, v120, v121
	v_cvt_pk_bf16_f32 v116, v4, v5
	v_cvt_pk_bf16_f32 v117, v6, v7
	v_mfma_f32_32x32x16_bf16 v[82:97], v[142:145], v[166:169], v[82:97]
	v_cvt_pk_bf16_f32 v118, v126, v127
	v_cvt_pk_bf16_f32 v119, v186, v187
	s_nop 0
	v_permlane32_swap_b32_e32 v228, v229
	v_permlane32_swap_b32_e32 v116, v118
	v_permlane32_swap_b32_e32 v117, v119
	v_mfma_f32_32x32x16_bf16 v[98:113], v[194:197], v[166:169], v[98:113]
	v_cvt_pk_bf16_f32 v134, v184, v185
	v_cvt_pk_bf16_f32 v135, v182, v183
	v_cvt_pk_bf16_f32 v136, v180, v181
	v_cvt_pk_bf16_f32 v137, v178, v179
	v_permlane32_swap_b32_e32 v128, v130
	v_permlane32_swap_b32_e32 v129, v131
	v_mfma_f32_32x32x16_bf16 v[82:97], v[230:233], v[162:165], v[82:97]
	v_permlane32_swap_b32_e32 v122, v124
	v_permlane32_swap_b32_e32 v123, v125
	v_permlane32_swap_b32_e32 v134, v136
	v_permlane32_swap_b32_e32 v135, v137
	s_waitcnt lgkmcnt(0)
	v_mfma_f32_32x32x16_bf16 v[98:113], v[238:241], v[162:165], v[98:113]
	v_add_u32_e32 v6, 32, v2
	v_mov_b32_e32 v7, v3
	v_lshlrev_b64 v[12:13], 10, v[2:3]
	v_lshlrev_b64 v[14:15], 10, v[6:7]
	v_lshl_add_u64 v[4:5], v[16:17], 0, v[12:13]
	v_lshl_add_u64 v[8:9], v[16:17], 0, v[14:15]
	v_lshl_add_u64 v[12:13], v[206:207], 0, v[12:13]
	global_load_dwordx4 v[4:7], v[4:5], off
	s_nop 0
	global_load_dwordx4 v[8:11], v[8:9], off
	v_lshl_add_u64 v[114:115], v[206:207], 0, v[14:15]
	global_load_dwordx4 v[12:15], v[12:13], off
	s_nop 0
	global_load_dwordx4 v[178:181], v[114:115], off
	ds_read_b64_tr_b16 v[138:139], v213 offset:0
	ds_read_b64_tr_b16 v[140:141], v213 offset:0x800
	ds_read_b64_tr_b16 v[142:143], v213 offset:0x1000
	ds_read_b64_tr_b16 v[144:145], v213 offset:0x1800
	ds_read_b64_tr_b16 v[182:183], v213 offset:0x2000
	ds_read_b64_tr_b16 v[184:185], v213 offset:0x2800
	ds_read_b64_tr_b16 v[186:187], v213 offset:0x3000
	ds_read_b64_tr_b16 v[188:189], v213 offset:0x3800
	s_waitcnt lgkmcnt(0)
; __device__ __forceinline__ void mask_bits(f32x16& p0, f32x16& p1, unsigned long long mk, int hi) {
;     const float NEG = -__builtin_inff();
;     const unsigned lo = (unsigned)mk >> (4 * hi), hh = (unsigned)(mk >> 32) >> (4 * hi);
; #pragma unroll
;     for (int r = 0; r < 16; ++r) {
;         const int c = (r & 3) + 8 * (r >> 2);
;         if (!(lo & (1u << c))) p0[r] = NEG;
;         if (!(hh & (1u << c))) p1[r] = NEG;
;     }
; }
; __device__ __forceinline__ void partialSM(f32x16& p0, f32x16& p1, float& m_reg, float& mn, float& alpha) {
;     float pmax = p0[0];
; #pragma unroll
;     for (int r = 1; r < 16; ++r) pmax = fmaxf(pmax, p0[r]);
; #pragma unroll
;     for (int r = 0; r < 16; ++r) pmax = fmaxf(pmax, p1[r]);
;     { auto rr = __builtin_amdgcn_permlane32_swap(__float_as_uint(pmax), __float_as_uint(pmax), false, false);
;       pmax = fmaxf(__uint_as_float(rr[0]), __uint_as_float(rr[1])); }
;     constexpr float C2 = 1.4426950408889634f * SM_SCALE;
;     if (__builtin_expect(__all((pmax - m_reg) * SM_SCALE <= THR), 1)) { mn = m_reg; alpha = 1.f; }
; template <int VB>
; __device__ __forceinline__ void pv_tile(f32x16* o, int vb0, bf16x8 pa0, bf16x8 pa1, bf16x8 pa2, bf16x8 pa3) {
;     ...
;     PV_D0(0); PV_D0(1); PV_D0(2); PV_D0(3);
	s_nop 0
	v_mfma_f32_32x32x16_bf16 v[66:81], v[128:131], v[138:141], v[66:81]
	ds_read_b64_tr_b16 v[138:139], v213 offset:0x200
	ds_read_b64_tr_b16 v[140:141], v213 offset:0xa00
	v_mfma_f32_32x32x16_bf16 v[66:81], v[122:125], v[142:145], v[66:81]
	ds_read_b64_tr_b16 v[142:143], v213 offset:0x1200
	ds_read_b64_tr_b16 v[144:145], v213 offset:0x1a00
	v_mfma_f32_32x32x16_bf16 v[66:81], v[116:119], v[182:185], v[66:81]
	ds_read_b64_tr_b16 v[182:183], v213 offset:0x2200
	ds_read_b64_tr_b16 v[184:185], v213 offset:0x2a00
	ds_read_b64_tr_b16 v[190:191], v213 offset:0x3200
	ds_read_b64_tr_b16 v[192:193], v213 offset:0x3a00
	s_waitcnt lgkmcnt(0)
	v_mfma_f32_32x32x16_bf16 v[66:81], v[134:137], v[186:189], v[66:81]
	v_mfma_f32_32x32x16_bf16 v[50:65], v[128:131], v[138:141], v[50:65]
	ds_read_b64_tr_b16 v[138:139], v213 offset:0x400
	ds_read_b64_tr_b16 v[140:141], v213 offset:0xc00
	v_mfma_f32_32x32x16_bf16 v[50:65], v[122:125], v[142:145], v[50:65]
	ds_read_b64_tr_b16 v[142:143], v213 offset:0x1400
	ds_read_b64_tr_b16 v[144:145], v213 offset:0x1c00
	v_mfma_f32_32x32x16_bf16 v[50:65], v[116:119], v[182:185], v[50:65]
	ds_read_b64_tr_b16 v[182:183], v213 offset:0x2400
	ds_read_b64_tr_b16 v[184:185], v213 offset:0x2c00
	ds_read_b64_tr_b16 v[186:187], v213 offset:0x3400
	ds_read_b64_tr_b16 v[188:189], v213 offset:0x3c00
	s_waitcnt lgkmcnt(0)
	v_mfma_f32_32x32x16_bf16 v[50:65], v[134:137], v[190:193], v[50:65]
	v_mfma_f32_32x32x16_bf16 v[34:49], v[128:131], v[138:141], v[34:49]
	ds_read_b64_tr_b16 v[138:139], v213 offset:0x600
	ds_read_b64_tr_b16 v[140:141], v213 offset:0xe00
	v_mfma_f32_32x32x16_bf16 v[34:49], v[122:125], v[142:145], v[34:49]
	ds_read_b64_tr_b16 v[142:143], v213 offset:0x1600
	ds_read_b64_tr_b16 v[144:145], v213 offset:0x1e00
	v_mfma_f32_32x32x16_bf16 v[34:49], v[116:119], v[182:185], v[34:49]
	ds_read_b64_tr_b16 v[182:183], v213 offset:0x2600
	ds_read_b64_tr_b16 v[184:185], v213 offset:0x2e00
	ds_read_b64_tr_b16 v[190:191], v213 offset:0x3600
	ds_read_b64_tr_b16 v[192:193], v213 offset:0x3e00
	s_waitcnt lgkmcnt(0)
	v_mfma_f32_32x32x16_bf16 v[34:49], v[134:137], v[186:189], v[34:49]
	s_waitcnt vmcnt(4)
	v_lshrrev_b32_e32 v120, v215, v132
	v_lshrrev_b32_e32 v121, v215, v133
	v_mfma_f32_32x32x16_bf16 v[18:33], v[128:131], v[138:141], v[18:33]
	v_bfe_i32 v114, v120, 0, 1
	v_bfi_b32 v114, v114, v82, v225
	v_mov_b32_e32 v230, 1.0
	v_bfe_i32 v1, v121, 0, 1
	v_bfi_b32 v1, v1, v98, v225
	v_mfma_f32_32x32x16_bf16 v[18:33], v[122:125], v[142:145], v[18:33]
	v_bfe_i32 v98, v120, 1, 1
	v_bfi_b32 v98, v98, v83, v225
	v_bfe_i32 v82, v121, 1, 1
	v_bfi_b32 v82, v82, v99, v225
	v_mfma_f32_32x32x16_bf16 v[18:33], v[116:119], v[182:185], v[18:33]
	v_bfe_i32 v99, v120, 2, 1
	v_bfi_b32 v99, v99, v84, v225
	v_bfe_i32 v83, v121, 2, 1
	v_bfi_b32 v83, v83, v100, v225
	v_mfma_f32_32x32x16_bf16 v[18:33], v[134:137], v[190:193], v[18:33]
	v_bfe_i32 v100, v120, 3, 1
	v_bfi_b32 v100, v100, v85, v225
	v_bfe_i32 v84, v121, 3, 1
	v_bfi_b32 v84, v84, v101, v225
	v_bfe_i32 v101, v120, 8, 1
	v_bfi_b32 v101, v101, v86, v225
	v_bfe_i32 v85, v121, 8, 1
	v_bfi_b32 v85, v85, v102, v225
	v_bfe_i32 v102, v120, 9, 1
	v_bfi_b32 v102, v102, v87, v225
	v_bfe_i32 v86, v121, 9, 1
	v_bfi_b32 v86, v86, v103, v225
	v_bfe_i32 v103, v120, 10, 1
	v_bfi_b32 v103, v103, v88, v225
	v_bfe_i32 v87, v121, 10, 1
	v_bfi_b32 v87, v87, v104, v225
	v_and_b32_e32 v104, 0x2000000, v120
	v_bfe_i32 v115, v120, 11, 1
	v_bfi_b32 v115, v115, v89, v225
	v_bfe_i32 v88, v121, 11, 1
	v_bfi_b32 v88, v88, v105, v225
	v_and_b32_e32 v105, 0x4000000, v120
	v_bfe_i32 v116, v120, 16, 1
	v_bfi_b32 v116, v116, v90, v225
	v_bfe_i32 v89, v121, 16, 1
	v_bfi_b32 v89, v89, v106, v225
	v_and_b32_e32 v106, 0x8000000, v120
	v_bfe_i32 v117, v120, 17, 1
	v_bfi_b32 v117, v117, v91, v225
	v_bfe_i32 v90, v121, 17, 1
	v_bfi_b32 v90, v90, v107, v225
	v_bfe_i32 v107, v120, 18, 1
	v_bfi_b32 v107, v107, v92, v225
	v_bfe_i32 v91, v121, 18, 1
	v_bfi_b32 v91, v91, v108, v225
	v_bfe_i32 v108, v120, 19, 1
	v_bfi_b32 v108, v108, v93, v225
	v_and_b32_e32 v93, 0x1000000, v120
	v_bfe_i32 v92, v121, 19, 1
	v_bfi_b32 v92, v92, v109, v225
	v_cmp_ne_u32_e32 vcc, 0, v93
	v_max_f32_e32 v109, v98, v98
	s_nop 1
	v_cndmask_b32_e32 v94, v225, v94, vcc
	v_bfe_i32 v93, v121, 24, 1
	v_bfi_b32 v93, v93, v110, v225
	v_max_f32_e32 v110, v114, v114
	v_max_f32_e32 v109, v110, v109
	v_cmp_ne_u32_e32 vcc, 0, v104
	v_max3_f32 v109, v109, v99, v100
	s_nop 1
	v_cndmask_b32_e32 v95, v225, v95, vcc
	v_max3_f32 v109, v109, v101, v102
	v_max3_f32 v109, v109, v103, v115
	v_bfe_i32 v104, v121, 25, 1
	v_bfi_b32 v104, v104, v111, v225
	v_cmp_ne_u32_e32 vcc, 0, v105
	v_max3_f32 v109, v109, v116, v117
	s_nop 1
	v_cndmask_b32_e32 v96, v225, v96, vcc
	v_max3_f32 v109, v109, v107, v108
	v_max3_f32 v109, v109, v94, v95
	v_bfe_i32 v105, v121, 26, 1
	v_bfi_b32 v105, v105, v112, v225
	v_cmp_ne_u32_e32 vcc, 0, v106
	s_nop 0
	s_nop 1
	v_cndmask_b32_e32 v97, v225, v97, vcc
	v_max3_f32 v109, v109, v96, v97
	v_max3_f32 v109, v109, v1, v82
	v_max3_f32 v109, v109, v83, v84
	v_max3_f32 v109, v109, v85, v86
	v_max3_f32 v109, v109, v87, v88
	v_max3_f32 v109, v109, v89, v90
	v_max3_f32 v109, v109, v91, v92
	v_max3_f32 v109, v109, v93, v104
	v_bfe_i32 v106, v121, 27, 1
	v_bfi_b32 v106, v106, v113, v225
	v_max3_f32 v109, v109, v105, v106
	v_mov_b32_e32 v110, v109
	s_nop 1
	v_permlane32_swap_b32_e32 v109, v110
	v_max_f32_e32 v110, v110, v110
	v_max_f32_e32 v109, v109, v109
	v_max_f32_e32 v109, v109, v110
	v_sub_f32_e32 v110, v109, v201
	v_mul_f32_e32 v110, 0x3db504f3, v110
	v_cmp_ge_f32_e32 vcc, s41, v110
	s_cmp_eq_u64 vcc, exec
	s_cbranch_scc0 .LBB0_1241

; template <int VB>
; __device__ __forceinline__ void pv_tile(f32x16* o, int vb0, bf16x8 pa0, bf16x8 pa1, bf16x8 pa2, bf16x8 pa3) {
;     ...
;     PV_D0(0); PV_D0(1); PV_D0(2); PV_D0(3);
.LBB0_1235:
	ds_read_b64_tr_b16 v[234:235], v213 offset:0x4000
	ds_read_b64_tr_b16 v[236:237], v213 offset:0x4800
	ds_read_b64_tr_b16 v[238:239], v213 offset:0x5000
	ds_read_b64_tr_b16 v[240:241], v213 offset:0x5800
	ds_read_b64_tr_b16 v[242:243], v213 offset:0x6000
	ds_read_b64_tr_b16 v[244:245], v213 offset:0x6800
	ds_read_b64_tr_b16 v[246:247], v213 offset:0x7000
	ds_read_b64_tr_b16 v[248:249], v213 offset:0x7800
	s_waitcnt lgkmcnt(0)
	s_nop 0
	v_mfma_f32_32x32x16_bf16 v[66:81], v[182:185], v[234:237], v[66:81]
	ds_read_b64_tr_b16 v[234:235], v213 offset:0x4200
	ds_read_b64_tr_b16 v[236:237], v213 offset:0x4a00
	v_mfma_f32_32x32x16_bf16 v[66:81], v[186:189], v[238:241], v[66:81]
	ds_read_b64_tr_b16 v[238:239], v213 offset:0x5200
	ds_read_b64_tr_b16 v[240:241], v213 offset:0x5a00
	v_mfma_f32_32x32x16_bf16 v[66:81], v[190:193], v[242:245], v[66:81]
	ds_read_b64_tr_b16 v[242:243], v213 offset:0x6200
	ds_read_b64_tr_b16 v[244:245], v213 offset:0x6a00
	ds_read_b64_tr_b16 v[250:251], v213 offset:0x7200
	ds_read_b64_tr_b16 v[252:253], v213 offset:0x7a00
	s_waitcnt lgkmcnt(0)
	v_mfma_f32_32x32x16_bf16 v[66:81], v[194:197], v[246:249], v[66:81]
	v_mfma_f32_32x32x16_bf16 v[50:65], v[182:185], v[234:237], v[50:65]
	ds_read_b64_tr_b16 v[234:235], v213 offset:0x4400
	ds_read_b64_tr_b16 v[236:237], v213 offset:0x4c00
	v_mfma_f32_32x32x16_bf16 v[50:65], v[186:189], v[238:241], v[50:65]
	ds_read_b64_tr_b16 v[238:239], v213 offset:0x5400
	ds_read_b64_tr_b16 v[240:241], v213 offset:0x5c00
	v_mfma_f32_32x32x16_bf16 v[50:65], v[190:193], v[242:245], v[50:65]
	ds_read_b64_tr_b16 v[242:243], v213 offset:0x6400
	ds_read_b64_tr_b16 v[244:245], v213 offset:0x6c00
	ds_read_b64_tr_b16 v[246:247], v213 offset:0x7400
	ds_read_b64_tr_b16 v[248:249], v213 offset:0x7c00
	s_waitcnt lgkmcnt(0)
	v_mfma_f32_32x32x16_bf16 v[50:65], v[194:197], v[250:253], v[50:65]
	v_mfma_f32_32x32x16_bf16 v[34:49], v[182:185], v[234:237], v[34:49]
	ds_read_b64_tr_b16 v[234:235], v213 offset:0x4600
	ds_read_b64_tr_b16 v[236:237], v213 offset:0x4e00
	v_mfma_f32_32x32x16_bf16 v[34:49], v[186:189], v[238:241], v[34:49]
	ds_read_b64_tr_b16 v[238:239], v213 offset:0x5600
	ds_read_b64_tr_b16 v[240:241], v213 offset:0x5e00
	v_mfma_f32_32x32x16_bf16 v[34:49], v[190:193], v[242:245], v[34:49]
	ds_read_b64_tr_b16 v[242:243], v213 offset:0x6600
	ds_read_b64_tr_b16 v[244:245], v213 offset:0x6e00
	ds_read_b64_tr_b16 v[250:251], v213 offset:0x7600
	ds_read_b64_tr_b16 v[252:253], v213 offset:0x7e00
	s_waitcnt lgkmcnt(0)
	v_mfma_f32_32x32x16_bf16 v[34:49], v[194:197], v[246:249], v[34:49]
	s_waitcnt vmcnt(0)
; __device__ __forceinline__ void mask_bits(f32x16& p0, f32x16& p1, unsigned long long mk, int hi) {
;     const float NEG = -__builtin_inff();
;     const unsigned lo = (unsigned)mk >> (4 * hi), hh = (unsigned)(mk >> 32) >> (4 * hi);
; #pragma unroll
;     for (int r = 0; r < 16; ++r) {
;         const int c = (r & 3) + 8 * (r >> 2);
;         if (!(lo & (1u << c))) p0[r] = NEG;
;         if (!(hh & (1u << c))) p1[r] = NEG;
;     }
; }
; __device__ __forceinline__ void partialSM(f32x16& p0, f32x16& p1, float& m_reg, float& mn, float& alpha) {
;     float pmax = p0[0];
; #pragma unroll
;     for (int r = 1; r < 16; ++r) pmax = fmaxf(pmax, p0[r]);
; #pragma unroll
;     for (int r = 0; r < 16; ++r) pmax = fmaxf(pmax, p1[r]);
;     { auto rr = __builtin_amdgcn_permlane32_swap(__float_as_uint(pmax), __float_as_uint(pmax), false, false);
;       pmax = fmaxf(__uint_as_float(rr[0]), __uint_as_float(rr[1])); }
;     constexpr float C2 = 1.4426950408889634f * SM_SCALE;
;     if (__builtin_expect(__all((pmax - m_reg) * SM_SCALE <= THR), 1)) { mn = m_reg; alpha = 1.f; }
	v_lshrrev_b32_e32 v218, v215, v204
	v_lshrrev_b32_e32 v233, v215, v205
	v_mfma_f32_32x32x16_bf16 v[18:33], v[182:185], v[234:237], v[18:33]
	v_bfe_i32 v1, v218, 0, 1
	v_bfi_b32 v1, v1, v130, v225
	v_and_b32_e32 v130, 1, v233
	v_cmp_eq_u32_e32 vcc, 1, v130
	v_and_b32_e32 v130, 2, v218
	v_max_f32_e32 v182, v1, v1
	s_nop 1
	v_cndmask_b32_e32 v114, v225, v114, vcc
	v_cmp_ne_u32_e32 vcc, 0, v130
	v_and_b32_e32 v130, 2, v233
	v_mfma_f32_32x32x16_bf16 v[18:33], v[186:189], v[238:241], v[18:33]
	s_nop 1
	v_cndmask_b32_e32 v131, v225, v131, vcc
	v_cmp_ne_u32_e32 vcc, 0, v130
	v_and_b32_e32 v130, 4, v218
	s_nop 0
	s_nop 1
	v_cndmask_b32_e32 v115, v225, v115, vcc
	v_cmp_ne_u32_e32 vcc, 0, v130
	v_and_b32_e32 v130, 4, v233
	v_mfma_f32_32x32x16_bf16 v[18:33], v[190:193], v[242:245], v[18:33]
	s_nop 1
	v_cndmask_b32_e32 v132, v225, v132, vcc
	v_cmp_ne_u32_e32 vcc, 0, v130
	v_and_b32_e32 v130, 8, v218
	s_nop 0
	s_nop 1
	v_cndmask_b32_e32 v116, v225, v116, vcc
	v_cmp_ne_u32_e32 vcc, 0, v130
	v_and_b32_e32 v130, 8, v233
	v_mfma_f32_32x32x16_bf16 v[18:33], v[194:197], v[250:253], v[18:33]
	s_nop 1
	v_cndmask_b32_e32 v133, v225, v133, vcc
	v_cmp_ne_u32_e32 vcc, 0, v130
	v_and_b32_e32 v130, 0x100, v218
	s_nop 0
	s_nop 1
	v_cndmask_b32_e32 v117, v225, v117, vcc
	v_cmp_ne_u32_e32 vcc, 0, v130
	v_and_b32_e32 v130, 0x100, v233
	s_nop 0
	s_nop 1
	v_cndmask_b32_e32 v134, v225, v134, vcc
	v_cmp_ne_u32_e32 vcc, 0, v130
	v_and_b32_e32 v130, 0x200, v218
	s_nop 0
	s_nop 1
	v_cndmask_b32_e32 v118, v225, v118, vcc
	v_cmp_ne_u32_e32 vcc, 0, v130
	v_and_b32_e32 v130, 0x200, v233
	s_nop 0
	s_nop 1
	v_cndmask_b32_e32 v135, v225, v135, vcc
	v_cmp_ne_u32_e32 vcc, 0, v130
	v_and_b32_e32 v130, 0x400, v218
	s_nop 0
	s_nop 1
	v_cndmask_b32_e32 v119, v225, v119, vcc
	v_cmp_ne_u32_e32 vcc, 0, v130
	v_and_b32_e32 v130, 0x400, v233
	s_nop 0
	s_nop 1
	v_cndmask_b32_e32 v136, v225, v136, vcc
	v_cmp_ne_u32_e32 vcc, 0, v130
	v_and_b32_e32 v130, 0x800, v218
	s_nop 0
	s_nop 1
	v_cndmask_b32_e32 v120, v225, v120, vcc
	v_cmp_ne_u32_e32 vcc, 0, v130
	v_and_b32_e32 v130, 0x800, v233
	s_nop 0
	s_nop 1
	v_cndmask_b32_e32 v137, v225, v137, vcc
	v_cmp_ne_u32_e32 vcc, 0, v130
	v_and_b32_e32 v130, 0x10000, v218
	s_nop 0
	s_nop 1
	v_cndmask_b32_e32 v121, v225, v121, vcc
	v_cmp_ne_u32_e32 vcc, 0, v130
	v_and_b32_e32 v130, 0x10000, v233
	s_nop 0
	s_nop 1
	v_cndmask_b32_e32 v138, v225, v138, vcc
	v_cmp_ne_u32_e32 vcc, 0, v130
	v_and_b32_e32 v130, 0x20000, v218
	s_nop 0
	s_nop 1
	v_cndmask_b32_e32 v122, v225, v122, vcc
	v_cmp_ne_u32_e32 vcc, 0, v130
	v_and_b32_e32 v130, 0x20000, v233
	s_nop 0
	s_nop 1
	v_cndmask_b32_e32 v139, v225, v139, vcc
	v_cmp_ne_u32_e32 vcc, 0, v130
	v_and_b32_e32 v130, 0x40000, v218
	s_nop 0
	s_nop 1
	v_cndmask_b32_e32 v123, v225, v123, vcc
	v_cmp_ne_u32_e32 vcc, 0, v130
	v_and_b32_e32 v130, 0x40000, v233
	s_nop 0
	s_nop 1
	v_cndmask_b32_e32 v140, v225, v140, vcc
	v_cmp_ne_u32_e32 vcc, 0, v130
	v_and_b32_e32 v130, 0x80000, v218
	s_nop 0
	s_nop 1
	v_cndmask_b32_e32 v124, v225, v124, vcc
	v_cmp_ne_u32_e32 vcc, 0, v130
	v_and_b32_e32 v130, 0x80000, v233
	s_nop 0
	s_nop 1
	v_cndmask_b32_e32 v141, v225, v141, vcc
	v_cmp_ne_u32_e32 vcc, 0, v130
	v_and_b32_e32 v130, 0x1000000, v218
	s_nop 0
	s_nop 1
	v_cndmask_b32_e32 v125, v225, v125, vcc
	v_cmp_ne_u32_e32 vcc, 0, v130
	v_and_b32_e32 v130, 0x1000000, v233
	s_nop 0
	s_nop 1
	v_cndmask_b32_e32 v142, v225, v142, vcc
	v_cmp_ne_u32_e32 vcc, 0, v130
	v_and_b32_e32 v130, 0x2000000, v218
	s_nop 0
	s_nop 1
	v_cndmask_b32_e32 v126, v225, v126, vcc
	v_cmp_ne_u32_e32 vcc, 0, v130
	v_and_b32_e32 v130, 0x2000000, v233
	s_nop 0
	s_nop 1
	v_cndmask_b32_e32 v143, v225, v143, vcc
	v_cmp_ne_u32_e32 vcc, 0, v130
	v_and_b32_e32 v130, 0x4000000, v218
	s_nop 0
	s_nop 1
	v_cndmask_b32_e32 v127, v225, v127, vcc
	v_cmp_ne_u32_e32 vcc, 0, v130
	v_and_b32_e32 v130, 0x4000000, v233
	s_nop 0
	s_nop 1
	v_cndmask_b32_e32 v144, v225, v144, vcc
	v_cmp_ne_u32_e32 vcc, 0, v130
	v_and_b32_e32 v130, 0x8000000, v218
	s_nop 0
	s_nop 1
	v_cndmask_b32_e32 v128, v225, v128, vcc
	v_cmp_ne_u32_e32 vcc, 0, v130
	v_and_b32_e32 v130, 0x8000000, v233
	s_nop 0
	s_nop 1
	v_cndmask_b32_e32 v145, v225, v145, vcc
	v_cmp_ne_u32_e32 vcc, 0, v130
	v_max_f32_e32 v130, v131, v131
	v_max_f32_e32 v130, v182, v130
	v_max3_f32 v130, v130, v132, v133
	v_max3_f32 v130, v130, v134, v135
	v_max3_f32 v130, v130, v136, v137
	v_max3_f32 v130, v130, v138, v139
	v_max3_f32 v130, v130, v140, v141
	v_max3_f32 v130, v130, v142, v143
	v_max3_f32 v130, v130, v144, v145
	v_max3_f32 v130, v130, v114, v115
	v_max3_f32 v130, v130, v116, v117
	v_max3_f32 v130, v130, v118, v119
	v_max3_f32 v130, v130, v120, v121
	v_max3_f32 v130, v130, v122, v123
	v_max3_f32 v130, v130, v124, v125
	s_nop 1
	v_cndmask_b32_e32 v129, v225, v129, vcc
	v_max3_f32 v130, v130, v126, v127
	v_max3_f32 v130, v130, v128, v129
	v_mov_b32_e32 v182, v130
	s_nop 1
	v_permlane32_swap_b32_e32 v130, v182
	v_max_f32_e32 v182, v182, v182
	v_max_f32_e32 v130, v130, v130
	v_max_f32_e32 v182, v130, v182
	v_sub_f32_e32 v130, v182, v201
	v_mul_f32_e32 v130, 0x3db504f3, v130
	v_cmp_ge_f32_e32 vcc, s41, v130
	s_cmp_eq_u64 vcc, exec
	v_mov_b32_e32 v130, 1.0
	s_cbranch_scc0 .LBB0_1242

; #define SBAR() do { asm volatile("s_waitcnt vmcnt(0) lgkmcnt(0)" ::: "memory"); __syncthreads(); } while (0)
; #define SBAR() __builtin_amdgcn_sched_barrier(0)
; __device__ __forceinline__ void finishSM(f32x16& p0, f32x16& p1, float alpha, float& l_reg, bf16x8& pa0, bf16x8& pa1, bf16x8& pa2, bf16x8& pa3) {
; #pragma unroll
;     for (int r = 0; r < 16; ++r) p1[r] = __builtin_amdgcn_exp2f(p1[r]);
;     float ps = 0;
; #pragma unroll
;     for (int r = 0; r < 16; ++r) ps += p0[r];
; #pragma unroll
;     for (int r = 0; r < 16; ++r) ps += p1[r];
;     { auto rr = __builtin_amdgcn_permlane32_swap(__float_as_uint(ps), __float_as_uint(ps), false, false);
;       ps = __uint_as_float(rr[0]) + __uint_as_float(rr[1]); }
;     l_reg = l_reg * alpha + ps;
;     ...
;     PK4(p0, 0, pa0); PK4(p0, 8, pa1); PK4(p1, 0, pa2); PK4(p1, 8, pa3);
; template <int MODE>
; __device__ __forceinline__ void block(const Ref& cur, const Ref& nxt, char* lds, Seam& S) {
;     ...
;     { const bf16_t* vp = nxt.V + (size_t)sre * PKV + sce; const bf16_t* kp = nxt.K + (size_t)sre * PKV + sce;
;       S.st_v0 = LD8(vp); S.st_v1 = LD8(vp + (size_t)32 * PKV); S.st_k0 = LD8(kp); S.st_k1 = LD8(kp + (size_t)32 * PKV); SBAR();
;       if (QPRE) { const bf16_t* qp = nxt.Q + qrow_off<MODE>(wid * QBLK + r32e) + hie * 8;
; #pragma unroll
;       for (int d0 = 0; d0 < 8; ++d0) S.qr[d0] = LD8(qp + d0 * 16); } }
;     SBAR();
;     finishSM(pA0, pA1, alA, l_reg, pa0, pa1, pa2, pa3); SBAR();
;     pv_tile<0>(o, vb0, pa0, pa1, pa2, pa3);
.LBB0_1247:
	v_ashrrev_i32_e32 v4, 4, v17
	v_ashrrev_i32_e32 v5, 31, v4
	v_lshlrev_b64 v[4:5], 10, v[4:5]
	v_lshlrev_b32_e32 v2, 4, v17
	v_lshl_add_u64 v[6:7], s[14:15], 0, v[4:5]
	v_and_b32_e32 v2, 0xf0, v2
	v_lshl_add_u64 v[6:7], v[6:7], 0, v[2:3]
	v_lshl_add_u64 v[4:5], s[12:13], 0, v[4:5]
	global_load_dwordx4 v[130:133], v[6:7], off
	v_add_co_u32_e32 v6, vcc, s36, v6
	v_lshl_add_u64 v[4:5], v[4:5], 0, v[2:3]
	s_nop 0
	v_addc_co_u32_e32 v7, vcc, 0, v7, vcc
	global_load_dwordx4 v[134:137], v[6:7], off
	global_load_dwordx4 v[138:141], v[4:5], off
	v_add_co_u32_e32 v4, vcc, s36, v4
	v_bfe_u32 v129, v17, 5, 1
	s_nop 0
	v_addc_co_u32_e32 v5, vcc, 0, v5, vcc
	global_load_dwordx4 v[142:145], v[4:5], off
	v_lshl_or_b32 v2, s44, 5, v16
	v_lshrrev_b32_e32 v2, 3, v2
	v_lshlrev_b64 v[4:5], 12, v[2:3]
	v_lshlrev_b32_e32 v2, 8, v16
	v_lshl_add_u64 v[4:5], s[4:5], 0, v[4:5]
	v_and_b32_e32 v2, 0x700, v2
	v_lshl_add_u64 v[4:5], v[4:5], 0, v[2:3]
	v_lshlrev_b32_e32 v2, 4, v129
	v_lshl_add_u64 v[4:5], v[4:5], 0, v[2:3]
	global_load_dwordx4 v[158:161], v[4:5], off
	global_load_dwordx4 v[154:157], v[4:5], off offset:32
	global_load_dwordx4 v[150:153], v[4:5], off offset:64
	global_load_dwordx4 v[146:149], v[4:5], off offset:96
	global_load_dwordx4 v[174:177], v[4:5], off offset:128
	global_load_dwordx4 v[170:173], v[4:5], off offset:160
	global_load_dwordx4 v[166:169], v[4:5], off offset:192
	global_load_dwordx4 v[162:165], v[4:5], off offset:224
	v_add_f32_e32 v2, 0, v128
	v_cvt_pk_bf16_f32 v4, v128, v1
	v_add_f32_e32 v1, v1, v2
	v_add_f32_e32 v1, v126, v1
	v_add_f32_e32 v1, v123, v1
	v_add_f32_e32 v1, v122, v1
	v_add_f32_e32 v1, v125, v1
	v_add_f32_e32 v1, v124, v1
	v_add_f32_e32 v1, v127, v1
	v_add_f32_e32 v1, v114, v1
	v_add_f32_e32 v1, v115, v1
	v_add_f32_e32 v1, v116, v1
	v_add_f32_e32 v1, v117, v1
	v_exp_f32_e32 v2, v192
	v_add_f32_e32 v1, v118, v1
	v_exp_f32_e32 v12, v193
	v_add_f32_e32 v1, v119, v1
	v_exp_f32_e32 v13, v190
	v_add_f32_e32 v1, v120, v1
	v_exp_f32_e32 v14, v191
	v_add_f32_e32 v1, v121, v1
	v_exp_f32_e32 v15, v188
	v_add_f32_e32 v1, v2, v1
	v_exp_f32_e32 v128, v189
	v_add_f32_e32 v1, v12, v1
	v_exp_f32_e32 v186, v186
	v_add_f32_e32 v1, v13, v1
	v_exp_f32_e32 v187, v187
	v_add_f32_e32 v1, v14, v1
	v_exp_f32_e32 v184, v184
	v_add_f32_e32 v1, v15, v1
	v_exp_f32_e32 v185, v185
	v_add_f32_e32 v1, v128, v1
	v_exp_f32_e32 v182, v182
	v_add_f32_e32 v1, v186, v1
	v_exp_f32_e32 v183, v183
	v_add_f32_e32 v1, v187, v1
	v_exp_f32_e32 v180, v180
	v_add_f32_e32 v1, v184, v1
	v_exp_f32_e32 v181, v181
	v_add_f32_e32 v1, v185, v1
	v_exp_f32_e32 v178, v178
	v_add_f32_e32 v1, v182, v1
	v_exp_f32_e32 v179, v179
	v_add_f32_e32 v1, v183, v1
	v_add_f32_e32 v1, v180, v1
	v_add_f32_e32 v1, v181, v1
	v_add_f32_e32 v1, v178, v1
	v_add_f32_e32 v1, v179, v1
	v_mov_b32_e32 v5, v1
	s_nop 1
	v_permlane32_swap_b32_e32 v1, v5
	v_add_f32_e32 v1, v1, v5
	v_fmac_f32_e32 v1, v199, v203
	v_cvt_pk_bf16_f32 v5, v126, v123
	v_cvt_pk_bf16_f32 v6, v122, v125
	v_cvt_pk_bf16_f32 v7, v124, v127
	v_cvt_pk_bf16_f32 v8, v114, v115
	v_cvt_pk_bf16_f32 v9, v116, v117
	v_cvt_pk_bf16_f32 v10, v118, v119
	v_cvt_pk_bf16_f32 v11, v120, v121
	v_cvt_pk_bf16_f32 v12, v2, v12
	v_cvt_pk_bf16_f32 v13, v13, v14
	v_cvt_pk_bf16_f32 v14, v15, v128
	v_cvt_pk_bf16_f32 v15, v186, v187
	v_cvt_pk_bf16_f32 v114, v184, v185
	v_cvt_pk_bf16_f32 v115, v182, v183
	v_cvt_pk_bf16_f32 v116, v180, v181
	v_cvt_pk_bf16_f32 v117, v178, v179
	s_nop 0
	v_permlane32_swap_b32_e32 v4, v6
	v_permlane32_swap_b32_e32 v5, v7
	v_permlane32_swap_b32_e32 v8, v10
	v_permlane32_swap_b32_e32 v9, v11
	v_permlane32_swap_b32_e32 v12, v14
	v_permlane32_swap_b32_e32 v13, v15
	v_permlane32_swap_b32_e32 v114, v116
	v_permlane32_swap_b32_e32 v115, v117
	ds_read_b64_tr_b16 v[118:119], v213 offset:0
	ds_read_b64_tr_b16 v[120:121], v213 offset:0x800
	ds_read_b64_tr_b16 v[122:123], v213 offset:0x1000
	ds_read_b64_tr_b16 v[124:125], v213 offset:0x1800
	ds_read_b64_tr_b16 v[178:179], v213 offset:0x2000
	ds_read_b64_tr_b16 v[180:181], v213 offset:0x2800
	ds_read_b64_tr_b16 v[182:183], v213 offset:0x3000
	ds_read_b64_tr_b16 v[184:185], v213 offset:0x3800
	s_waitcnt lgkmcnt(0)
	s_nop 0
	v_mfma_f32_32x32x16_bf16 v[66:81], v[4:7], v[118:121], v[66:81]
	ds_read_b64_tr_b16 v[118:119], v213 offset:0x200
	ds_read_b64_tr_b16 v[120:121], v213 offset:0xa00
	v_mfma_f32_32x32x16_bf16 v[66:81], v[8:11], v[122:125], v[66:81]
	ds_read_b64_tr_b16 v[122:123], v213 offset:0x1200
	ds_read_b64_tr_b16 v[124:125], v213 offset:0x1a00
	v_mfma_f32_32x32x16_bf16 v[66:81], v[12:15], v[178:181], v[66:81]
	ds_read_b64_tr_b16 v[178:179], v213 offset:0x2200
	ds_read_b64_tr_b16 v[180:181], v213 offset:0x2a00
	ds_read_b64_tr_b16 v[186:187], v213 offset:0x3200
	ds_read_b64_tr_b16 v[188:189], v213 offset:0x3a00
	s_waitcnt lgkmcnt(0)
	v_mfma_f32_32x32x16_bf16 v[66:81], v[114:117], v[182:185], v[66:81]
	v_mfma_f32_32x32x16_bf16 v[50:65], v[4:7], v[118:121], v[50:65]
	ds_read_b64_tr_b16 v[118:119], v213 offset:0x400
	ds_read_b64_tr_b16 v[120:121], v213 offset:0xc00
	v_mfma_f32_32x32x16_bf16 v[50:65], v[8:11], v[122:125], v[50:65]
	ds_read_b64_tr_b16 v[122:123], v213 offset:0x1400
	ds_read_b64_tr_b16 v[124:125], v213 offset:0x1c00
	v_mfma_f32_32x32x16_bf16 v[50:65], v[12:15], v[178:181], v[50:65]
	ds_read_b64_tr_b16 v[178:179], v213 offset:0x2400
	ds_read_b64_tr_b16 v[180:181], v213 offset:0x2c00
	ds_read_b64_tr_b16 v[182:183], v213 offset:0x3400
	ds_read_b64_tr_b16 v[184:185], v213 offset:0x3c00
	s_waitcnt lgkmcnt(0)
	v_mfma_f32_32x32x16_bf16 v[50:65], v[114:117], v[186:189], v[50:65]
	v_mfma_f32_32x32x16_bf16 v[34:49], v[4:7], v[118:121], v[34:49]
	ds_read_b64_tr_b16 v[118:119], v213 offset:0x600
	ds_read_b64_tr_b16 v[120:121], v213 offset:0xe00
	v_mfma_f32_32x32x16_bf16 v[34:49], v[8:11], v[122:125], v[34:49]
	ds_read_b64_tr_b16 v[122:123], v213 offset:0x1600
	ds_read_b64_tr_b16 v[124:125], v213 offset:0x1e00
	v_mfma_f32_32x32x16_bf16 v[34:49], v[12:15], v[178:181], v[34:49]
	ds_read_b64_tr_b16 v[178:179], v213 offset:0x2600
	ds_read_b64_tr_b16 v[180:181], v213 offset:0x2e00
	ds_read_b64_tr_b16 v[186:187], v213 offset:0x3600
	ds_read_b64_tr_b16 v[188:189], v213 offset:0x3e00
	s_waitcnt lgkmcnt(0)
	v_mfma_f32_32x32x16_bf16 v[34:49], v[114:117], v[182:185], v[34:49]
	v_mfma_f32_32x32x16_bf16 v[18:33], v[4:7], v[118:121], v[18:33]
	s_andn2_b64 vcc, exec, s[24:25]
	v_mfma_f32_32x32x16_bf16 v[18:33], v[8:11], v[122:125], v[18:33]
	v_mfma_f32_32x32x16_bf16 v[18:33], v[12:15], v[178:181], v[18:33]
	v_mfma_f32_32x32x16_bf16 v[18:33], v[114:117], v[186:189], v[18:33]
	s_cbranch_vccnz .LBB0_1254
; __device__ __forceinline__ void mask_bits(f32x16& p0, f32x16& p1, unsigned long long mk, int hi) {
;     const float NEG = -__builtin_inff();
;     const unsigned lo = (unsigned)mk >> (4 * hi), hh = (unsigned)(mk >> 32) >> (4 * hi);
; #pragma unroll
;     for (int r = 0; r < 16; ++r) {
;         const int c = (r & 3) + 8 * (r >> 2);
;         if (!(lo & (1u << c))) p0[r] = NEG;
;         if (!(hh & (1u << c))) p1[r] = NEG;
;     }
; }
; __device__ __forceinline__ void partialSM(f32x16& p0, f32x16& p1, float& m_reg, float& mn, float& alpha) {
;     float pmax = p0[0];
; #pragma unroll
;     for (int r = 1; r < 16; ++r) pmax = fmaxf(pmax, p0[r]);
; #pragma unroll
;     for (int r = 0; r < 16; ++r) pmax = fmaxf(pmax, p1[r]);
;     { auto rr = __builtin_amdgcn_permlane32_swap(__float_as_uint(pmax), __float_as_uint(pmax), false, false);
;       pmax = fmaxf(__uint_as_float(rr[0]), __uint_as_float(rr[1])); }
;     constexpr float C2 = 1.4426950408889634f * SM_SCALE;
;     if (__builtin_expect(__all((pmax - m_reg) * SM_SCALE <= THR), 1)) { mn = m_reg; alpha = 1.f; }
;     else { mn = fmaxf(m_reg, pmax); alpha = __builtin_amdgcn_exp2f((m_reg - mn) * C2); m_reg = mn; }
;     const float mnL = -mn * C2;
; #pragma unroll
;     for (int r = 0; r < 16; ++r) p0[r] = fmaf(p0[r], C2, mnL);
; #pragma unroll
;     for (int r = 0; r < 16; ++r) p1[r] = fmaf(p1[r], C2, mnL);
; #pragma unroll
;     for (int r = 0; r < 16; ++r) p0[r] = __builtin_amdgcn_exp2f(p0[r]);
; }
	s_waitcnt vmcnt(12)
	v_lshrrev_b32_e32 v114, v215, v204
	v_lshrrev_b32_e32 v115, v215, v205
	v_bfe_i32 v6, v114, 0, 1
	v_bfi_b32 v6, v6, v82, v225
	v_bfe_i32 v2, v115, 0, 1
	v_bfi_b32 v2, v2, v98, v225
	v_bfe_i32 v8, v114, 1, 1
	v_bfi_b32 v8, v8, v83, v225
	v_bfe_i32 v4, v115, 1, 1
	v_bfi_b32 v4, v4, v99, v225
	v_bfe_i32 v10, v114, 2, 1
	v_bfi_b32 v10, v10, v84, v225
	v_bfe_i32 v5, v115, 2, 1
	v_bfi_b32 v5, v5, v100, v225
	v_bfe_i32 v12, v114, 3, 1
	v_bfi_b32 v12, v12, v85, v225
	v_bfe_i32 v7, v115, 3, 1
	v_bfi_b32 v7, v7, v101, v225
	v_bfe_i32 v14, v114, 8, 1
	v_bfi_b32 v14, v14, v86, v225
	v_bfe_i32 v9, v115, 8, 1
	v_bfi_b32 v9, v9, v102, v225
	v_max_f32_e32 v102, v6, v6
	v_bfe_i32 v83, v114, 9, 1
	v_bfi_b32 v83, v83, v87, v225
	v_bfe_i32 v11, v115, 9, 1
	v_bfi_b32 v11, v11, v103, v225
	v_bfe_i32 v85, v114, 10, 1
	v_bfi_b32 v85, v85, v88, v225
	v_bfe_i32 v13, v115, 10, 1
	v_bfi_b32 v13, v13, v104, v225
	v_bfe_i32 v88, v114, 11, 1
	v_bfi_b32 v88, v88, v89, v225
	v_bfe_i32 v15, v115, 11, 1
	v_bfi_b32 v15, v15, v105, v225
	v_bfe_i32 v98, v114, 16, 1
	v_bfi_b32 v98, v98, v90, v225
	v_bfe_i32 v84, v115, 16, 1
	v_bfi_b32 v84, v84, v106, v225
	v_bfe_i32 v99, v114, 17, 1
	v_bfi_b32 v99, v99, v91, v225
	v_bfe_i32 v86, v115, 17, 1
	v_bfi_b32 v86, v86, v107, v225
	v_bfe_i32 v100, v114, 18, 1
	v_bfi_b32 v100, v100, v92, v225
	v_bfe_i32 v89, v115, 18, 1
	v_bfi_b32 v89, v89, v108, v225
	v_bfe_i32 v101, v114, 19, 1
	v_bfi_b32 v101, v101, v93, v225
	v_and_b32_e32 v82, 0x1000000, v114
	v_bfe_i32 v91, v115, 19, 1
	v_bfi_b32 v91, v91, v109, v225
	v_cmp_ne_u32_e32 vcc, 0, v82
	s_nop 0
	s_nop 1
	v_cndmask_b32_e32 v94, v225, v94, vcc
	v_and_b32_e32 v82, 0x2000000, v114
	v_bfe_i32 v93, v115, 24, 1
	v_bfi_b32 v93, v93, v110, v225
	v_cmp_ne_u32_e32 vcc, 0, v82
	s_nop 0
	s_nop 1
	v_cndmask_b32_e32 v95, v225, v95, vcc
	v_and_b32_e32 v82, 0x4000000, v114
	v_bfe_i32 v87, v115, 25, 1
	v_bfi_b32 v87, v87, v111, v225
	v_cmp_ne_u32_e32 vcc, 0, v82
	s_nop 0
	s_nop 1
	v_cndmask_b32_e32 v96, v225, v96, vcc
	v_and_b32_e32 v82, 0x8000000, v114
	v_bfe_i32 v90, v115, 26, 1
	v_bfi_b32 v90, v90, v112, v225
	v_cmp_ne_u32_e32 vcc, 0, v82
	s_nop 0
	s_nop 1
	v_cndmask_b32_e32 v97, v225, v97, vcc
	v_max_f32_e32 v82, v8, v8
	v_max_f32_e32 v82, v102, v82
	v_max3_f32 v82, v82, v10, v12
	v_max3_f32 v82, v82, v14, v83
	v_max3_f32 v82, v82, v85, v88
	v_max3_f32 v82, v82, v98, v99
	v_max3_f32 v82, v82, v100, v101
	v_max3_f32 v82, v82, v94, v95
	v_max3_f32 v82, v82, v96, v97
	v_max3_f32 v82, v82, v2, v4
	v_max3_f32 v82, v82, v5, v7
	v_max3_f32 v82, v82, v9, v11
	v_max3_f32 v82, v82, v13, v15
	v_max3_f32 v82, v82, v84, v86
	v_max3_f32 v82, v82, v89, v91
	v_bfe_i32 v92, v115, 27, 1
	v_bfi_b32 v92, v92, v113, v225
	v_max3_f32 v82, v82, v93, v87
	v_max3_f32 v82, v82, v90, v92
	v_mov_b32_e32 v102, v82
	s_nop 1
	v_permlane32_swap_b32_e32 v82, v102
	v_max_f32_e32 v102, v102, v102
	v_max_f32_e32 v82, v82, v82
	v_max_f32_e32 v102, v82, v102
	v_sub_f32_e32 v82, v102, v201
	v_mul_f32_e32 v82, 0x3db504f3, v82
	v_cmp_ge_f32_e32 vcc, s41, v82
	s_cmp_eq_u64 vcc, exec
	v_mov_b32_e32 v82, 1.0
	s_cbranch_scc0 .LBB0_1385
